# fourth XCD-local seam: layer-0 MLP-out to layer-1 in-proj uses the XCD-local barrier (same row-panel ownership), global barrier kept before the final norm
# speedup vs baseline: 1.0051x; 1.0051x over previous
.LBB0_1474:
	s_andn2_saveexec_b64 s[4:5], s[4:5]
	s_cbranch_execz .LBB0_1490
	v_mov_b32_e32 v0, 0x23fd4
	ds_read_b32 v0, v0
	v_readlane_b32 s5, v255, 21
	s_waitcnt lgkmcnt(0)
	v_readfirstlane_b32 s4, v0
	s_nop 3
	s_or_b32 s4, s4, s5
	s_cmp_eq_u32 s4, 0
	s_cbranch_scc1 .Lxcd_local_d
	v_readlane_b32 s4, v254, 61
	buffer_wbl2 sc1
	s_waitcnt lgkmcnt(0)
	s_waitcnt vmcnt(0)
	v_readlane_b32 s5, v254, 62
	v_mov_b32_e32 v0, 1
	v_sub_u32_e32 v4, 0, v2
	s_mov_b64 s[18:19], -1
	s_nop 1
	global_atomic_add v3, v1, v0, s[4:5] sc0
	v_cvt_f32_u32_e32 v0, v2
	v_readlane_b32 s4, v254, 63
	v_readlane_b32 s5, v255, 0
	v_rcp_iflag_f32_e32 v0, v0
	s_nop 0
	v_mul_f32_e32 v0, 0x4f7ffffe, v0
	v_cvt_u32_f32_e32 v0, v0
	v_mul_lo_u32 v4, v4, v0
	v_mul_hi_u32 v4, v0, v4
	v_add_u32_e32 v0, v0, v4
	s_waitcnt vmcnt(0)
	v_mul_hi_u32 v0, v3, v0
	v_mul_lo_u32 v4, v0, v2
	v_sub_u32_e32 v4, v3, v4
	v_cmp_ge_u32_e32 vcc, v4, v2
	v_add_u32_e32 v5, 1, v0
	v_add_u32_e32 v3, 1, v3
	v_cndmask_b32_e32 v0, v0, v5, vcc
	v_sub_u32_e32 v5, v4, v2
	v_cndmask_b32_e32 v4, v4, v5, vcc
	v_cmp_ge_u32_e32 vcc, v4, v2
	v_add_u32_e32 v4, 1, v0
	s_nop 0
	v_cndmask_b32_e32 v0, v0, v4, vcc
	v_mul_lo_u32 v4, v2, v0
	v_add_u32_e32 v2, v4, v2
	v_cmp_ne_u32_e32 vcc, v3, v2
	v_mov_b64_e32 v[2:3], s[4:5]
	s_and_saveexec_b64 s[4:5], vcc
	s_cbranch_execz .LBB0_1487
	v_readlane_b32 s8, v254, 63
	v_readlane_b32 s9, v255, 0
	s_mov_b64 s[28:29], 0
	s_nop 3
	global_load_dword v2, v1, s[8:9] sc1
	s_waitcnt vmcnt(0)
	v_cmp_eq_u32_e32 vcc, v2, v0
	s_and_saveexec_b64 s[18:19], vcc
	s_cbranch_execz .LBB0_1486
	s_mov_b32 s1, 1
	s_mov_b64 s[30:31], 0
	s_branch .LBB0_1479
